# grid barrier: buffer_inv issued before polling (both leader and non-leader paths) so invalidate latency overlaps the wait
# speedup vs baseline: 1.0115x; 1.0115x over previous
; __device__ __forceinline__ unsigned xb_ld(unsigned* p)              { return __hip_atomic_load(p, __ATOMIC_RELAXED, __HIP_MEMORY_SCOPE_AGENT); }
; __device__ __forceinline__ unsigned xb_add(unsigned* p, unsigned v) { return __hip_atomic_fetch_add(p, v, __ATOMIC_RELAXED, __HIP_MEMORY_SCOPE_AGENT); }
; #define XB_SPIN(cond, bar) do { unsigned _sp = 0; while (cond) { __builtin_amdgcn_s_sleep(1); \
;     if ((++_sp & 255u) == 0u) { if (xb_ld(&(bar)[XB_TMO])) break; if (_sp > XB_SPIN_CAP) { atomicAdd(&(bar)[XB_TMO], 1u); break; } } } } while (0)
; __device__ __forceinline__ void xcd_barrier(const XcdBarrier& b, int xb_tid) {
;     ...
;         const unsigned old = xb_add(&bar[XB_XSUB(b.x)], 1u);
;         const unsigned gen = old / nloc;
;         if (old + 1u == (gen + 1u) * nloc) {
;             __builtin_amdgcn_fence(__ATOMIC_RELEASE, "agent");
;             asm volatile("s_waitcnt vmcnt(0)" ::: "memory");
;             const unsigned og = xb_add(&bar[XB_TOP], 1u);
;             const unsigned tg = og / nx;
;             if (og + 1u == (tg + 1u) * nx) xb_add(&bar[XB_TOPGEN], 1u);
;             else XB_SPIN(xb_ld(&bar[XB_TOPGEN]) == tg, bar);
;             __builtin_amdgcn_fence(__ATOMIC_ACQUIRE, "agent");
;             xb_add(&bar[XB_XGEN(b.x)], 1u);
;             asm volatile("s_waitcnt vmcnt(0)" ::: "memory");
;         } else {
;             XB_SPIN(xb_ld(&bar[XB_XGEN(b.x)]) == gen, bar);
;             __builtin_amdgcn_fence(__ATOMIC_ACQUIRE, "agent");
.LBB0_137:
	s_or_b64 exec, exec, s[8:9]
	v_cvt_f32_u32_e32 v4, v2
	s_waitcnt vmcnt(0)
	v_readfirstlane_b32 s4, v3
	v_sub_u32_e32 v3, 0, v2
	v_rcp_iflag_f32_e32 v4, v4
	v_add_u32_e32 v5, s4, v1
	v_mul_f32_e32 v4, 0x4f7ffffe, v4
	v_cvt_u32_f32_e32 v4, v4
	v_mul_lo_u32 v1, v3, v4
	v_mul_hi_u32 v1, v4, v1
	v_add_u32_e32 v1, v4, v1
	v_mul_hi_u32 v1, v5, v1
	v_mul_lo_u32 v3, v1, v2
	v_sub_u32_e32 v3, v5, v3
	v_add_u32_e32 v4, 1, v1
	v_cmp_ge_u32_e32 vcc, v3, v2
	s_nop 1
	v_cndmask_b32_e32 v1, v1, v4, vcc
	v_sub_u32_e32 v4, v3, v2
	v_cndmask_b32_e32 v3, v3, v4, vcc
	v_add_u32_e32 v4, 1, v1
	v_cmp_ge_u32_e32 vcc, v3, v2
	v_add_u32_e32 v3, 1, v5
	s_nop 0
	v_cndmask_b32_e32 v1, v1, v4, vcc
	v_mul_lo_u32 v4, v2, v1
	v_add_u32_e32 v2, v4, v2
	v_cmp_ne_u32_e32 vcc, v3, v2
	s_and_saveexec_b64 s[4:5], vcc
	s_xor_b64 s[4:5], exec, s[4:5]
	s_cbranch_execz .LBB0_151
	s_waitcnt lgkmcnt(0)
	v_mov_b32_e32 v0, 0x2000
	buffer_inv sc1
	global_load_dword v0, v0, s[2:3] offset:1024 sc1
	s_add_u32 s12, s2, 0x2400
	s_addc_u32 s13, s3, 0
	s_waitcnt vmcnt(0)
	v_cmp_eq_u32_e32 vcc, v0, v1
	s_and_saveexec_b64 s[8:9], vcc
	s_cbranch_execz .LBB0_150
	v_readlane_b32 s16, v252, 1
	v_readlane_b32 s20, v252, 5
	v_readlane_b32 s21, v252, 6
	s_add_u32 s10, s20, 0x17ae0200
	v_readlane_b32 s17, v252, 2
	s_addc_u32 s11, s21, 0
	s_mov_b32 s34, 1
	s_mov_b64 s[14:15], 0
	v_mov_b32_e32 v0, 0
	v_readlane_b32 s18, v252, 3
	v_readlane_b32 s19, v252, 4
	v_readlane_b32 s22, v252, 7
	v_readlane_b32 s23, v252, 8
	s_branch .LBB0_141

; __device__ __forceinline__ unsigned xb_ld(unsigned* p)              { return __hip_atomic_load(p, __ATOMIC_RELAXED, __HIP_MEMORY_SCOPE_AGENT); }
; __device__ __forceinline__ unsigned xb_add(unsigned* p, unsigned v) { return __hip_atomic_fetch_add(p, v, __ATOMIC_RELAXED, __HIP_MEMORY_SCOPE_AGENT); }
; #define XB_SPIN(cond, bar) do { unsigned _sp = 0; while (cond) { __builtin_amdgcn_s_sleep(1); \
;     if ((++_sp & 255u) == 0u) { if (xb_ld(&(bar)[XB_TMO])) break; if (_sp > XB_SPIN_CAP) { atomicAdd(&(bar)[XB_TMO], 1u); break; } } } } while (0)
; __device__ __forceinline__ void xcd_barrier(const XcdBarrier& b, int xb_tid) {
;     ...
;             __builtin_amdgcn_fence(__ATOMIC_RELEASE, "agent");
;             asm volatile("s_waitcnt vmcnt(0)" ::: "memory");
;             const unsigned og = xb_add(&bar[XB_TOP], 1u);
;             const unsigned tg = og / nx;
;             if (og + 1u == (tg + 1u) * nx) xb_add(&bar[XB_TOPGEN], 1u);
;     ...
;             XB_SPIN(xb_ld(&bar[XB_XGEN(b.x)]) == gen, bar);
;             __builtin_amdgcn_fence(__ATOMIC_ACQUIRE, "agent");
;             asm volatile("s_waitcnt vmcnt(0)" ::: "memory");
.LBB0_150:
	s_or_b64 exec, exec, s[8:9]
	s_waitcnt vmcnt(0)
	s_waitcnt vmcnt(0)
.LBB0_151:
	s_andn2_saveexec_b64 s[4:5], s[4:5]
	s_cbranch_execz .LBB0_171
	s_mov_b64 s[4:5], exec
	buffer_wbl2 sc1
	s_waitcnt lgkmcnt(0)
	s_waitcnt vmcnt(0)
	buffer_inv sc1
	v_mbcnt_lo_u32_b32 v1, s4, 0
	v_mbcnt_hi_u32_b32 v1, s5, v1
	v_cmp_eq_u32_e32 vcc, 0, v1
	s_and_saveexec_b64 s[8:9], vcc
	s_cbranch_execz .LBB0_154
	s_bcnt1_i32_b64 s4, s[4:5]
	v_readlane_b32 s12, v252, 1
	v_mov_b32_e32 v2, 0x17ae3000
	v_mov_b32_e32 v3, s4
	v_readlane_b32 s16, v252, 5
	v_readlane_b32 s17, v252, 6
	v_readlane_b32 s13, v252, 2
	v_readlane_b32 s14, v252, 3
	v_readlane_b32 s15, v252, 4
	v_readlane_b32 s18, v252, 7
	v_readlane_b32 s19, v252, 8
	global_atomic_add v2, v2, v3, s[16:17] offset:1024 sc0

; __device__ __forceinline__ unsigned xb_ld(unsigned* p)              { return __hip_atomic_load(p, __ATOMIC_RELAXED, __HIP_MEMORY_SCOPE_AGENT); }
; __device__ __forceinline__ unsigned xb_add(unsigned* p, unsigned v) { return __hip_atomic_fetch_add(p, v, __ATOMIC_RELAXED, __HIP_MEMORY_SCOPE_AGENT); }
; #define XB_SPIN(cond, bar) do { unsigned _sp = 0; while (cond) { __builtin_amdgcn_s_sleep(1); \
;     if ((++_sp & 255u) == 0u) { if (xb_ld(&(bar)[XB_TMO])) break; if (_sp > XB_SPIN_CAP) { atomicAdd(&(bar)[XB_TMO], 1u); break; } } } } while (0)
; __device__ __forceinline__ void xcd_barrier(const XcdBarrier& b, int xb_tid) {
;     ...
;             if (og + 1u == (tg + 1u) * nx) xb_add(&bar[XB_TOPGEN], 1u);
;             else XB_SPIN(xb_ld(&bar[XB_TOPGEN]) == tg, bar);
;             __builtin_amdgcn_fence(__ATOMIC_ACQUIRE, "agent");
;             xb_add(&bar[XB_XGEN(b.x)], 1u);
;             asm volatile("s_waitcnt vmcnt(0)" ::: "memory");
.LBB0_168:
	s_or_b64 exec, exec, s[4:5]
	s_mov_b64 s[4:5], exec
	v_mbcnt_lo_u32_b32 v0, s4, 0
	v_mbcnt_hi_u32_b32 v0, s5, v0
	v_cmp_eq_u32_e32 vcc, 0, v0
	s_waitcnt vmcnt(0)
	s_and_saveexec_b64 s[8:9], vcc
	s_cbranch_execz .LBB0_170
	s_bcnt1_i32_b64 s4, s[4:5]
	v_mov_b32_e32 v0, 0x2000
	v_mov_b32_e32 v1, s4
	global_atomic_add v0, v1, s[2:3] offset:1024

; __device__ __forceinline__ unsigned xb_ld(unsigned* p)              { return __hip_atomic_load(p, __ATOMIC_RELAXED, __HIP_MEMORY_SCOPE_AGENT); }
; __device__ __forceinline__ unsigned xb_add(unsigned* p, unsigned v) { return __hip_atomic_fetch_add(p, v, __ATOMIC_RELAXED, __HIP_MEMORY_SCOPE_AGENT); }
; #define XB_SPIN(cond, bar) do { unsigned _sp = 0; while (cond) { __builtin_amdgcn_s_sleep(1); \
;     if ((++_sp & 255u) == 0u) { if (xb_ld(&(bar)[XB_TMO])) break; if (_sp > XB_SPIN_CAP) { atomicAdd(&(bar)[XB_TMO], 1u); break; } } } } while (0)
; __device__ __forceinline__ void xcd_barrier(const XcdBarrier& b, int xb_tid) {
;     ...
;         const unsigned old = xb_add(&bar[XB_XSUB(b.x)], 1u);
;         const unsigned gen = old / nloc;
;         if (old + 1u == (gen + 1u) * nloc) {
;             __builtin_amdgcn_fence(__ATOMIC_RELEASE, "agent");
;             asm volatile("s_waitcnt vmcnt(0)" ::: "memory");
;             const unsigned og = xb_add(&bar[XB_TOP], 1u);
;             const unsigned tg = og / nx;
;             if (og + 1u == (tg + 1u) * nx) xb_add(&bar[XB_TOPGEN], 1u);
;             else XB_SPIN(xb_ld(&bar[XB_TOPGEN]) == tg, bar);
;             __builtin_amdgcn_fence(__ATOMIC_ACQUIRE, "agent");
;             xb_add(&bar[XB_XGEN(b.x)], 1u);
;             asm volatile("s_waitcnt vmcnt(0)" ::: "memory");
;         } else {
;             XB_SPIN(xb_ld(&bar[XB_XGEN(b.x)]) == gen, bar);
;             __builtin_amdgcn_fence(__ATOMIC_ACQUIRE, "agent");
.LBB0_916:
	s_or_b64 exec, exec, s[0:1]
	v_cvt_f32_u32_e32 v4, v2
	s_waitcnt vmcnt(0)
	v_readfirstlane_b32 s0, v3
	v_sub_u32_e32 v3, 0, v2
	v_rcp_iflag_f32_e32 v4, v4
	v_add_u32_e32 v5, s0, v1
	v_mul_f32_e32 v4, 0x4f7ffffe, v4
	v_cvt_u32_f32_e32 v4, v4
	v_mul_lo_u32 v1, v3, v4
	v_mul_hi_u32 v1, v4, v1
	v_add_u32_e32 v1, v4, v1
	v_mul_hi_u32 v1, v5, v1
	v_mul_lo_u32 v3, v1, v2
	v_sub_u32_e32 v3, v5, v3
	v_add_u32_e32 v4, 1, v1
	v_cmp_ge_u32_e32 vcc, v3, v2
	s_nop 1
	v_cndmask_b32_e32 v1, v1, v4, vcc
	v_sub_u32_e32 v4, v3, v2
	v_cndmask_b32_e32 v3, v3, v4, vcc
	v_add_u32_e32 v4, 1, v1
	v_cmp_ge_u32_e32 vcc, v3, v2
	v_add_u32_e32 v3, 1, v5
	s_nop 0
	v_cndmask_b32_e32 v1, v1, v4, vcc
	v_mul_lo_u32 v4, v2, v1
	v_add_u32_e32 v2, v4, v2
	v_cmp_ne_u32_e32 vcc, v3, v2
	s_and_saveexec_b64 s[0:1], vcc
	s_xor_b64 s[4:5], exec, s[0:1]
	s_cbranch_execz .LBB0_930
	v_readlane_b32 s0, v255, 23
	v_readlane_b32 s1, v255, 24
	s_waitcnt lgkmcnt(0)
	s_nop 3
	buffer_inv sc1
	global_load_dword v0, v81, s[0:1] sc1
	s_waitcnt vmcnt(0)
	v_cmp_eq_u32_e32 vcc, v0, v1
	s_and_saveexec_b64 s[8:9], vcc
	s_cbranch_execz .LBB0_929
	s_mov_b32 s36, 1
	s_mov_b64 s[0:1], 0
	s_branch .LBB0_920

; __device__ __forceinline__ unsigned xb_add(unsigned* p, unsigned v) { return __hip_atomic_fetch_add(p, v, __ATOMIC_RELAXED, __HIP_MEMORY_SCOPE_AGENT); }
; __device__ __forceinline__ void xcd_barrier(const XcdBarrier& b, int xb_tid) {
;     ...
;             __builtin_amdgcn_fence(__ATOMIC_RELEASE, "agent");
;             asm volatile("s_waitcnt vmcnt(0)" ::: "memory");
;             const unsigned og = xb_add(&bar[XB_TOP], 1u);
;             const unsigned tg = og / nx;
;             if (og + 1u == (tg + 1u) * nx) xb_add(&bar[XB_TOPGEN], 1u);
.LBB0_930:
	s_andn2_saveexec_b64 s[0:1], s[4:5]
	s_cbranch_execz .LBB0_950
	s_mov_b64 s[0:1], exec
	buffer_wbl2 sc1
	s_waitcnt lgkmcnt(0)
	s_waitcnt vmcnt(0)
	buffer_inv sc1
	v_mbcnt_lo_u32_b32 v1, s0, 0
	v_mbcnt_hi_u32_b32 v1, s1, v1
	v_cmp_eq_u32_e32 vcc, 0, v1
	s_and_saveexec_b64 s[4:5], vcc
	s_cbranch_execz .LBB0_933
	s_bcnt1_i32_b64 s0, s[0:1]
	v_mov_b32_e32 v2, s0
	v_readlane_b32 s0, v255, 25
	v_readlane_b32 s1, v255, 26
	s_nop 4
	global_atomic_add v2, v81, v2, s[0:1] sc0

; __device__ __forceinline__ unsigned xb_ld(unsigned* p)              { return __hip_atomic_load(p, __ATOMIC_RELAXED, __HIP_MEMORY_SCOPE_AGENT); }
; __device__ __forceinline__ unsigned xb_add(unsigned* p, unsigned v) { return __hip_atomic_fetch_add(p, v, __ATOMIC_RELAXED, __HIP_MEMORY_SCOPE_AGENT); }
; #define XB_SPIN(cond, bar) do { unsigned _sp = 0; while (cond) { __builtin_amdgcn_s_sleep(1); \
;     if ((++_sp & 255u) == 0u) { if (xb_ld(&(bar)[XB_TMO])) break; if (_sp > XB_SPIN_CAP) { atomicAdd(&(bar)[XB_TMO], 1u); break; } } } } while (0)
; __device__ __forceinline__ void xcd_barrier(const XcdBarrier& b, int xb_tid) {
;     ...
;             if (og + 1u == (tg + 1u) * nx) xb_add(&bar[XB_TOPGEN], 1u);
;             else XB_SPIN(xb_ld(&bar[XB_TOPGEN]) == tg, bar);
;             __builtin_amdgcn_fence(__ATOMIC_ACQUIRE, "agent");
;             xb_add(&bar[XB_XGEN(b.x)], 1u);
;             asm volatile("s_waitcnt vmcnt(0)" ::: "memory");
.LBB0_947:
	s_or_b64 exec, exec, s[4:5]
	s_mov_b64 s[0:1], exec
	v_mbcnt_lo_u32_b32 v0, s0, 0
	v_mbcnt_hi_u32_b32 v0, s1, v0
	v_cmp_eq_u32_e32 vcc, 0, v0
	s_waitcnt vmcnt(0)
	s_and_saveexec_b64 s[4:5], vcc
	s_cbranch_execz .LBB0_949
	s_bcnt1_i32_b64 s0, s[0:1]
	v_mov_b32_e32 v0, s0
	v_readlane_b32 s0, v255, 23
	v_readlane_b32 s1, v255, 24
	s_nop 4
	global_atomic_add v81, v0, s[0:1]

; __device__ __forceinline__ unsigned xb_ld(unsigned* p)              { return __hip_atomic_load(p, __ATOMIC_RELAXED, __HIP_MEMORY_SCOPE_AGENT); }
; __device__ __forceinline__ unsigned xb_add(unsigned* p, unsigned v) { return __hip_atomic_fetch_add(p, v, __ATOMIC_RELAXED, __HIP_MEMORY_SCOPE_AGENT); }
; #define XB_SPIN(cond, bar) do { unsigned _sp = 0; while (cond) { __builtin_amdgcn_s_sleep(1); \
;     if ((++_sp & 255u) == 0u) { if (xb_ld(&(bar)[XB_TMO])) break; if (_sp > XB_SPIN_CAP) { atomicAdd(&(bar)[XB_TMO], 1u); break; } } } } while (0)
; __device__ __forceinline__ void xcd_barrier(const XcdBarrier& b, int xb_tid) {
;     ...
;         const unsigned old = xb_add(&bar[XB_XSUB(b.x)], 1u);
;         const unsigned gen = old / nloc;
;         if (old + 1u == (gen + 1u) * nloc) {
;             __builtin_amdgcn_fence(__ATOMIC_RELEASE, "agent");
;             asm volatile("s_waitcnt vmcnt(0)" ::: "memory");
;             const unsigned og = xb_add(&bar[XB_TOP], 1u);
;             const unsigned tg = og / nx;
;             if (og + 1u == (tg + 1u) * nx) xb_add(&bar[XB_TOPGEN], 1u);
;             else XB_SPIN(xb_ld(&bar[XB_TOPGEN]) == tg, bar);
;             __builtin_amdgcn_fence(__ATOMIC_ACQUIRE, "agent");
;             xb_add(&bar[XB_XGEN(b.x)], 1u);
;             asm volatile("s_waitcnt vmcnt(0)" ::: "memory");
;         } else {
;             XB_SPIN(xb_ld(&bar[XB_XGEN(b.x)]) == gen, bar);
;             __builtin_amdgcn_fence(__ATOMIC_ACQUIRE, "agent");
.LBB0_1376:
	s_or_b64 exec, exec, s[0:1]
	v_cvt_f32_u32_e32 v4, v2
	s_waitcnt vmcnt(0)
	v_readfirstlane_b32 s0, v3
	v_sub_u32_e32 v3, 0, v2
	v_rcp_iflag_f32_e32 v4, v4
	v_add_u32_e32 v5, s0, v1
	v_mul_f32_e32 v4, 0x4f7ffffe, v4
	v_cvt_u32_f32_e32 v4, v4
	v_mul_lo_u32 v1, v3, v4
	v_mul_hi_u32 v1, v4, v1
	v_add_u32_e32 v1, v4, v1
	v_mul_hi_u32 v1, v5, v1
	v_mul_lo_u32 v3, v1, v2
	v_sub_u32_e32 v3, v5, v3
	v_add_u32_e32 v4, 1, v1
	v_cmp_ge_u32_e32 vcc, v3, v2
	s_nop 1
	v_cndmask_b32_e32 v1, v1, v4, vcc
	v_sub_u32_e32 v4, v3, v2
	v_cndmask_b32_e32 v3, v3, v4, vcc
	v_add_u32_e32 v4, 1, v1
	v_cmp_ge_u32_e32 vcc, v3, v2
	v_add_u32_e32 v3, 1, v5
	s_nop 0
	v_cndmask_b32_e32 v1, v1, v4, vcc
	v_mul_lo_u32 v4, v2, v1
	v_add_u32_e32 v2, v4, v2
	v_cmp_ne_u32_e32 vcc, v3, v2
	s_and_saveexec_b64 s[0:1], vcc
	s_xor_b64 s[4:5], exec, s[0:1]
	s_cbranch_execz .LBB0_1390
	v_readlane_b32 s0, v255, 23
	v_readlane_b32 s1, v255, 24
	s_waitcnt lgkmcnt(0)
	s_nop 3
	buffer_inv sc1
	global_load_dword v0, v81, s[0:1] sc1
	s_waitcnt vmcnt(0)
	v_cmp_eq_u32_e32 vcc, v0, v1
	s_and_saveexec_b64 s[8:9], vcc
	s_cbranch_execz .LBB0_1389
	s_mov_b32 s38, 1
	s_mov_b64 s[0:1], 0
	s_branch .LBB0_1380

; __device__ __forceinline__ unsigned xb_add(unsigned* p, unsigned v) { return __hip_atomic_fetch_add(p, v, __ATOMIC_RELAXED, __HIP_MEMORY_SCOPE_AGENT); }
; __device__ __forceinline__ void xcd_barrier(const XcdBarrier& b, int xb_tid) {
;     ...
;             __builtin_amdgcn_fence(__ATOMIC_RELEASE, "agent");
;             asm volatile("s_waitcnt vmcnt(0)" ::: "memory");
;             const unsigned og = xb_add(&bar[XB_TOP], 1u);
;             const unsigned tg = og / nx;
;             if (og + 1u == (tg + 1u) * nx) xb_add(&bar[XB_TOPGEN], 1u);
.LBB0_1798:
	s_mov_b64 s[0:1], exec
	buffer_wbl2 sc1
	s_waitcnt lgkmcnt(0)
	s_waitcnt vmcnt(0)
	buffer_inv sc1
	v_mbcnt_lo_u32_b32 v1, s0, 0
	v_mbcnt_hi_u32_b32 v1, s1, v1
	v_cmp_eq_u32_e32 vcc, 0, v1
	s_and_saveexec_b64 s[4:5], vcc
	s_cbranch_execz .LBB0_1800
	s_bcnt1_i32_b64 s0, s[0:1]
	v_mov_b32_e32 v2, s0
	v_readlane_b32 s0, v255, 25
	v_readlane_b32 s1, v255, 26
	s_nop 4
	global_atomic_add v2, v81, v2, s[0:1] sc0

; __device__ __forceinline__ unsigned xb_ld(unsigned* p)              { return __hip_atomic_load(p, __ATOMIC_RELAXED, __HIP_MEMORY_SCOPE_AGENT); }
; __device__ __forceinline__ unsigned xb_add(unsigned* p, unsigned v) { return __hip_atomic_fetch_add(p, v, __ATOMIC_RELAXED, __HIP_MEMORY_SCOPE_AGENT); }
; #define XB_SPIN(cond, bar) do { unsigned _sp = 0; while (cond) { __builtin_amdgcn_s_sleep(1); \
;     if ((++_sp & 255u) == 0u) { if (xb_ld(&(bar)[XB_TMO])) break; if (_sp > XB_SPIN_CAP) { atomicAdd(&(bar)[XB_TMO], 1u); break; } } } } while (0)
; __device__ __forceinline__ void xcd_barrier(const XcdBarrier& b, int xb_tid) {
;     ...
;             if (og + 1u == (tg + 1u) * nx) xb_add(&bar[XB_TOPGEN], 1u);
;             else XB_SPIN(xb_ld(&bar[XB_TOPGEN]) == tg, bar);
;             __builtin_amdgcn_fence(__ATOMIC_ACQUIRE, "agent");
;             xb_add(&bar[XB_XGEN(b.x)], 1u);
;             asm volatile("s_waitcnt vmcnt(0)" ::: "memory");
.LBB0_1814:
	s_or_b64 exec, exec, s[4:5]
	s_mov_b64 s[0:1], exec
	v_mbcnt_lo_u32_b32 v0, s0, 0
	v_mbcnt_hi_u32_b32 v0, s1, v0
	v_cmp_eq_u32_e32 vcc, 0, v0
	s_waitcnt vmcnt(0)
	s_and_saveexec_b64 s[4:5], vcc
	s_cbranch_execnz .LBB0_1815
	s_getpc_b64 s[98:99]
